# phase 10 row loop: all four rows of a batch loaded before the single wait (rows 3-4 were fetched only after rows 1-2 had arrived)
# baseline (speedup 1.0000x reference)
; DI float bflo(unsigned u) { return __uint_as_float(u << 16); }
; DI float bfhi(unsigned u) { return __uint_as_float(u & 0xffff0000u); }
; DI void final_norm_b(const Params& p) {
;     ...
;     for (int row0 = gw; row0 < NLAT; row0 += 4 * NGW) {
;         u32x4 v[4][2];
; #pragma unroll
;         for (int u = 0; u < 4; ++u)
; #pragma unroll
;             for (int j = 0; j < 2; ++j) v[u][j] = *(const u32x4*)(X2 + (size_t)(row0 + u * NGW) * DM + 8 * lane + 512 * j);
; #pragma unroll
;         for (int u = 0; u < 4; ++u) {
;             const int row = row0 + u * NGW;
;             f32x4 f[2][2]; float s = 0.f;
; #pragma unroll
;             for (int j = 0; j < 2; ++j) { const u32x4 q = v[u][j];
;                 f[j][0] = (f32x4){bflo(q.x), bfhi(q.x), bflo(q.y), bfhi(q.y)}; f[j][1] = (f32x4){bflo(q.z), bfhi(q.z), bflo(q.w), bfhi(q.w)};
;                 s += (f[j][0].x * f[j][0].x + f[j][0].y * f[j][0].y) + (f[j][0].z * f[j][0].z + f[j][0].w * f[j][0].w) + (f[j][1].x * f[j][1].x + f[j][1].y * f[j][1].y) + (f[j][1].z * f[j][1].z + f[j][1].w * f[j][1].w); }
.LBB0_990:
	v_ashrrev_i32_e32 v45, 31, v44
	v_lshlrev_b64 v[22:23], 11, v[44:45]
	v_lshl_add_u64 v[22:23], v[16:17], 0, v[22:23]
	global_load_dwordx4 v[26:29], v[22:23], off offset:1024
	global_load_dwordx4 v[30:33], v[22:23], off
	v_add_u32_e32 v22, s12, v44
	v_ashrrev_i32_e32 v23, 31, v22
	v_lshlrev_b64 v[24:25], 11, v[22:23]
	v_lshl_add_u64 v[24:25], v[16:17], 0, v[24:25]
	global_load_dwordx4 v[38:41], v[24:25], off offset:1024
	global_load_dwordx4 v[52:55], v[24:25], off
	v_add_u32_e32 v100, s13, v44
	v_ashrrev_i32_e32 v101, 31, v100
	v_lshlrev_b64 v[100:101], 11, v[100:101]
	v_lshl_add_u64 v[100:101], v[16:17], 0, v[100:101]
	global_load_dwordx4 v[104:107], v[100:101], off offset:1024
	global_load_dwordx4 v[108:111], v[100:101], off
	v_add_u32_e32 v102, s14, v44
	v_ashrrev_i32_e32 v103, 31, v102
	v_lshlrev_b64 v[102:103], 11, v[102:103]
	v_lshl_add_u64 v[102:103], v[16:17], 0, v[102:103]
	global_load_dwordx4 v[112:115], v[102:103], off
	global_load_dwordx4 v[116:119], v[102:103], off offset:1024
	v_add_u32_e32 v24, s13, v44
	v_ashrrev_i32_e32 v25, 31, v24
	s_waitcnt vmcnt(0)
	v_and_b32_e32 v71, 0xffff0000, v26
	v_and_b32_e32 v70, 0xffff0000, v30
	v_and_b32_e32 v75, 0xffff0000, v27
	v_and_b32_e32 v74, 0xffff0000, v31
	v_and_b32_e32 v79, 0xffff0000, v28
	v_and_b32_e32 v78, 0xffff0000, v32
	v_and_b32_e32 v83, 0xffff0000, v29
	v_and_b32_e32 v82, 0xffff0000, v33
	v_lshlrev_b32_e32 v69, 16, v26
	v_lshlrev_b32_e32 v68, 16, v30
	v_lshlrev_b32_e32 v73, 16, v27
	v_lshlrev_b32_e32 v72, 16, v31
	v_lshlrev_b32_e32 v77, 16, v28
	v_lshlrev_b32_e32 v76, 16, v32
	v_lshlrev_b32_e32 v81, 16, v29
	v_lshlrev_b32_e32 v80, 16, v33
	v_pk_mul_f32 v[26:27], v[70:71], v[70:71]
	v_pk_mul_f32 v[56:57], v[74:75], v[74:75]
	v_pk_mul_f32 v[58:59], v[78:79], v[78:79]
	v_pk_mul_f32 v[60:61], v[82:83], v[82:83]
	v_and_b32_e32 v29, 0xffff0000, v38
	v_and_b32_e32 v28, 0xffff0000, v52
	v_and_b32_e32 v43, 0xffff0000, v39
	v_and_b32_e32 v42, 0xffff0000, v53
	v_lshlrev_b32_e32 v35, 16, v38
	v_lshlrev_b32_e32 v34, 16, v52
	v_lshlrev_b32_e32 v37, 16, v39
	v_lshlrev_b32_e32 v36, 16, v53
	v_lshlrev_b32_e32 v31, 16, v40
	v_lshlrev_b32_e32 v30, 16, v54
	v_and_b32_e32 v39, 0xffff0000, v40
	v_and_b32_e32 v38, 0xffff0000, v54
	v_lshlrev_b32_e32 v32, 16, v55
	v_and_b32_e32 v40, 0xffff0000, v55
	v_pk_fma_f32 v[26:27], v[68:69], v[68:69], v[26:27]
	v_pk_fma_f32 v[52:53], v[72:73], v[72:73], v[56:57]
	v_pk_fma_f32 v[54:55], v[76:77], v[76:77], v[58:59]
	v_pk_fma_f32 v[56:57], v[80:81], v[80:81], v[60:61]
	v_pk_mul_f32 v[58:59], v[28:29], v[28:29]
	v_pk_mul_f32 v[60:61], v[42:43], v[42:43]
	v_lshlrev_b32_e32 v33, 16, v41
	v_and_b32_e32 v41, 0xffff0000, v41
	v_pk_mul_f32 v[62:63], v[38:39], v[38:39]
	v_pk_add_f32 v[26:27], v[26:27], v[52:53]
	v_pk_fma_f32 v[52:53], v[34:35], v[34:35], v[58:59]
	v_pk_fma_f32 v[58:59], v[36:37], v[36:37], v[60:61]
	v_pk_mul_f32 v[64:65], v[40:41], v[40:41]
	v_pk_fma_f32 v[60:61], v[30:31], v[30:31], v[62:63]
	v_pk_add_f32 v[52:53], v[52:53], v[58:59]
	v_pk_fma_f32 v[62:63], v[32:33], v[32:33], v[64:65]
	v_pk_add_f32 v[26:27], v[54:55], v[26:27]
	v_pk_add_f32 v[52:53], v[60:61], v[52:53]
	v_pk_add_f32 v[26:27], v[56:57], v[26:27]
	v_pk_add_f32 v[52:53], v[62:63], v[52:53]
	v_mov_b32_e32 v55, v26
	v_mov_b32_e32 v54, v52
	v_mov_b32_e32 v26, v53
	v_pk_add_f32 v[26:27], v[54:55], v[26:27]
	s_nop 1
	v_mov_b32_dpp v61, v27 quad_perm:[1,0,3,2] row_mask:0xf bank_mask:0xf
	s_nop 1
	v_mov_b32_dpp v60, v26 quad_perm:[1,0,3,2] row_mask:0xf bank_mask:0xf
	v_lshlrev_b64 v[52:53], 11, v[24:25]
	v_lshl_add_u64 v[62:63], v[16:17], 0, v[52:53]
	v_mov_b64_e32 v[52:53], v[104:105]
	v_mov_b64_e32 v[54:55], v[106:107]
	v_mov_b64_e32 v[56:57], v[108:109]
	v_mov_b64_e32 v[58:59], v[110:111]
	v_mov_b32_e32 v90, v72
	s_waitcnt lgkmcnt(0)
	v_pk_add_f32 v[60:61], v[26:27], v[60:61]
	s_nop 1
	v_mov_b32_dpp v63, v61 quad_perm:[2,3,0,1] row_mask:0xf bank_mask:0xf
	s_nop 1
	v_mov_b32_dpp v62, v60 quad_perm:[2,3,0,1] row_mask:0xf bank_mask:0xf
	v_add_u32_e32 v26, s14, v44
	v_ashrrev_i32_e32 v27, 31, v26
	v_lshlrev_b64 v[64:65], 11, v[26:27]
	v_lshl_add_u64 v[88:89], v[16:17], 0, v[64:65]
	s_waitcnt lgkmcnt(0)
	v_pk_add_f32 v[84:85], v[60:61], v[62:63]
	v_mov_b64_e32 v[60:61], v[112:113]
	v_mov_b64_e32 v[62:63], v[114:115]
	v_mov_b64_e32 v[64:65], v[116:117]
	v_mov_b64_e32 v[66:67], v[118:119]
	s_nop 1
	v_mov_b32_dpp v87, v85 row_half_mirror row_mask:0xf bank_mask:0xf
	s_nop 1
	v_mov_b32_dpp v86, v84 row_half_mirror row_mask:0xf bank_mask:0xf
	v_mov_b32_e32 v88, v68
	v_mov_b32_e32 v89, v70
	v_mov_b32_e32 v70, v69
	v_mov_b32_e32 v91, v74
	s_waitcnt lgkmcnt(0)
	v_pk_add_f32 v[84:85], v[84:85], v[86:87]
	s_nop 1
	v_mov_b32_dpp v87, v85 row_ror:8 row_mask:0xf bank_mask:0xf
	s_nop 1
	v_mov_b32_dpp v86, v84 row_ror:8 row_mask:0xf bank_mask:0xf
	v_lshlrev_b64 v[44:45], 12, v[44:45]
	v_mov_b32_e32 v92, v76
	v_mov_b32_e32 v93, v78
	v_mov_b32_e32 v94, v80
	s_waitcnt lgkmcnt(0)
	v_pk_add_f32 v[84:85], v[84:85], v[86:87]
	ds_bpermute_b32 v87, v50, v85
	ds_bpermute_b32 v86, v50, v84
	v_mov_b32_e32 v95, v82
	v_mov_b32_e32 v74, v73
	v_mov_b32_e32 v78, v77
	v_mov_b32_e32 v82, v81
	s_waitcnt lgkmcnt(0)
	v_pk_add_f32 v[84:85], v[84:85], v[86:87]
	ds_bpermute_b32 v87, v51, v85
	ds_bpermute_b32 v86, v51, v84
	v_lshl_add_u64 v[44:45], v[18:19], 0, v[44:45]
	v_lshlrev_b64 v[24:25], 12, v[24:25]
	v_lshl_add_u64 v[24:25], v[18:19], 0, v[24:25]
	s_waitcnt lgkmcnt(0)
	v_pk_add_f32 v[68:69], v[84:85], v[86:87]
	s_nop 0
	v_pk_fma_f32 v[68:69], v[68:69], s[8:9], v[20:21] op_sel_hi:[1,0,0]
	s_waitcnt vmcnt(0)
; DI float bflo(unsigned u) { return __uint_as_float(u << 16); }
; DI float bfhi(unsigned u) { return __uint_as_float(u & 0xffff0000u); }
; DI void final_norm_b(const Params& p) {
;     ...
;         for (int u = 0; u < 4; ++u) {
;             const int row = row0 + u * NGW;
;             f32x4 f[2][2]; float s = 0.f;
; #pragma unroll
;             for (int j = 0; j < 2; ++j) { const u32x4 q = v[u][j];
;                 f[j][0] = (f32x4){bflo(q.x), bfhi(q.x), bflo(q.y), bfhi(q.y)}; f[j][1] = (f32x4){bflo(q.z), bfhi(q.z), bflo(q.w), bfhi(q.w)};
;                 s += (f[j][0].x * f[j][0].x + f[j][0].y * f[j][0].y) + (f[j][0].z * f[j][0].z + f[j][0].w * f[j][0].w) + (f[j][1].x * f[j][1].x + f[j][1].y * f[j][1].y) + (f[j][1].z * f[j][1].z + f[j][1].w * f[j][1].w); }
;             const float rstd = rsqrtf(wave_sum(s) * (1.f / DM) + EPS);
;             float* dst = p.out + (size_t)row * DM + 8 * lane;
; #pragma unroll
;             for (int j = 0; j < 2; ++j) { *(f32x4*)(dst + 512 * j) = f[j][0] * rstd * gn[j][0]; *(f32x4*)(dst + 512 * j + 4) = f[j][1] * rstd * gn[j][1]; }
	v_and_b32_e32 v97, 0xffff0000, v67
	v_mul_f32_e32 v72, 0x4b800000, v69
	v_cmp_gt_f32_e32 vcc, s15, v69
	v_cmp_gt_f32_e64 s[0:1], s15, v68
	s_nop 0
	v_cndmask_b32_e32 v69, v69, v72, vcc
	v_rsq_f32_e32 v69, v69
	v_mul_f32_e32 v72, 0x4b800000, v68
	v_cndmask_b32_e64 v96, v68, v72, s[0:1]
	v_mul_f32_e32 v68, 0x45800000, v69
	v_cndmask_b32_e32 v68, v69, v68, vcc
	v_pk_mul_f32 v[72:73], v[88:89], v[68:69] op_sel_hi:[1,0]
	v_pk_mul_f32 v[76:77], v[90:91], v[68:69] op_sel_hi:[1,0]
	v_pk_mul_f32 v[86:87], v[70:71], v[68:69] op_sel_hi:[1,0]
	v_pk_mul_f32 v[80:81], v[92:93], v[68:69] op_sel_hi:[1,0]
	v_pk_mul_f32 v[84:85], v[94:95], v[68:69] op_sel_hi:[1,0]
	v_pk_mul_f32 v[88:89], v[74:75], v[68:69] op_sel_hi:[1,0]
	v_pk_mul_f32 v[90:91], v[78:79], v[68:69] op_sel_hi:[1,0]
	v_pk_mul_f32 v[82:83], v[82:83], v[68:69] op_sel_hi:[1,0]
	v_pk_mul_f32 v[70:71], v[6:7], v[76:77]
	v_pk_mul_f32 v[68:69], v[4:5], v[72:73]
	v_pk_mul_f32 v[76:77], v[12:13], v[86:87]
	v_pk_mul_f32 v[74:75], v[2:3], v[84:85]
	v_pk_mul_f32 v[72:73], v[0:1], v[80:81]
	v_pk_mul_f32 v[78:79], v[14:15], v[88:89]
	global_store_dwordx4 v[44:45], v[68:71], off
	global_store_dwordx4 v[44:45], v[72:75], off offset:16
	global_store_dwordx4 v[44:45], v[76:79], off offset:2048
	v_and_b32_e32 v81, 0xffff0000, v53
	v_and_b32_e32 v80, 0xffff0000, v57
	v_and_b32_e32 v77, 0xffff0000, v52
	v_and_b32_e32 v76, 0xffff0000, v56
	v_pk_mul_f32 v[70:71], v[10:11], v[82:83]
	v_lshlrev_b32_e32 v75, 16, v52
	v_lshlrev_b32_e32 v74, 16, v56
	v_lshlrev_b32_e32 v79, 16, v53
	v_lshlrev_b32_e32 v78, 16, v57
	v_lshlrev_b32_e32 v57, 16, v54
	v_and_b32_e32 v83, 0xffff0000, v54
	v_lshlrev_b32_e32 v85, 16, v55
	v_and_b32_e32 v87, 0xffff0000, v55
	v_pk_mul_f32 v[52:53], v[76:77], v[76:77]
	v_pk_mul_f32 v[54:55], v[80:81], v[80:81]
	v_and_b32_e32 v82, 0xffff0000, v58
	v_pk_fma_f32 v[52:53], v[74:75], v[74:75], v[52:53]
	v_pk_fma_f32 v[54:55], v[78:79], v[78:79], v[54:55]
	v_lshlrev_b32_e32 v56, 16, v58
	v_pk_add_f32 v[52:53], v[52:53], v[54:55]
	v_pk_mul_f32 v[54:55], v[82:83], v[82:83]
	v_and_b32_e32 v86, 0xffff0000, v59
	v_pk_fma_f32 v[54:55], v[56:57], v[56:57], v[54:55]
	v_lshlrev_b32_e32 v84, 16, v59
	v_pk_add_f32 v[52:53], v[54:55], v[52:53]
	v_pk_mul_f32 v[54:55], v[86:87], v[86:87]
	v_pk_mul_f32 v[68:69], v[8:9], v[90:91]
	v_pk_fma_f32 v[54:55], v[84:85], v[84:85], v[54:55]
	v_lshlrev_b32_e32 v59, 16, v64
	v_and_b32_e32 v89, 0xffff0000, v64
	v_and_b32_e32 v88, 0xffff0000, v60
	v_lshlrev_b32_e32 v91, 16, v65
	v_and_b32_e32 v65, 0xffff0000, v65
	v_and_b32_e32 v64, 0xffff0000, v61
	v_rsq_f32_e32 v72, v96
	v_pk_add_f32 v[52:53], v[54:55], v[52:53]
	v_lshlrev_b32_e32 v58, 16, v60
	v_lshlrev_b32_e32 v90, 16, v61
	v_lshlrev_b32_e32 v60, 16, v62
	v_and_b32_e32 v92, 0xffff0000, v62
	v_lshlrev_b32_e32 v94, 16, v63
	v_and_b32_e32 v96, 0xffff0000, v63
	v_pk_mul_f32 v[54:55], v[88:89], v[88:89]
	v_pk_mul_f32 v[62:63], v[64:65], v[64:65]
	v_and_b32_e32 v93, 0xffff0000, v66
	v_pk_fma_f32 v[54:55], v[58:59], v[58:59], v[54:55]
	v_pk_fma_f32 v[62:63], v[90:91], v[90:91], v[62:63]
	v_lshlrev_b32_e32 v61, 16, v66
	v_pk_add_f32 v[54:55], v[54:55], v[62:63]
	v_pk_mul_f32 v[62:63], v[92:93], v[92:93]
	v_lshlrev_b32_e32 v95, 16, v67
	v_pk_fma_f32 v[62:63], v[60:61], v[60:61], v[62:63]
	global_store_dwordx4 v[44:45], v[68:71], off offset:2064
	v_pk_add_f32 v[54:55], v[62:63], v[54:55]
	v_pk_mul_f32 v[62:63], v[96:97], v[96:97]
	v_mul_f32_e32 v44, 0x45800000, v72
	v_pk_fma_f32 v[62:63], v[94:95], v[94:95], v[62:63]
	v_lshlrev_b64 v[68:69], 12, v[22:23]
	v_pk_add_f32 v[54:55], v[62:63], v[54:55]
	v_mov_b32_e32 v63, v52
	v_mov_b32_e32 v62, v54
	v_mov_b32_e32 v52, v55
	v_pk_add_f32 v[52:53], v[62:63], v[52:53]
	s_nop 1
	v_mov_b32_dpp v55, v53 quad_perm:[1,0,3,2] row_mask:0xf bank_mask:0xf
	s_nop 1
	v_mov_b32_dpp v54, v52 quad_perm:[1,0,3,2] row_mask:0xf bank_mask:0xf
	v_cndmask_b32_e64 v44, v72, v44, s[0:1]
	v_lshl_add_u64 v[70:71], v[18:19], 0, v[68:69]
	v_mov_b32_e32 v68, v34
	v_mov_b32_e32 v69, v28
	s_waitcnt lgkmcnt(0)
	v_pk_add_f32 v[52:53], v[52:53], v[54:55]
	s_nop 1
	v_mov_b32_dpp v55, v53 quad_perm:[2,3,0,1] row_mask:0xf bank_mask:0xf
	s_nop 1
	v_mov_b32_dpp v54, v52 quad_perm:[2,3,0,1] row_mask:0xf bank_mask:0xf
	v_pk_mul_f32 v[72:73], v[68:69], v[44:45] op_sel_hi:[1,0]
	v_mov_b32_e32 v68, v36
	v_mov_b32_e32 v69, v42
	v_pk_mul_f32 v[68:69], v[68:69], v[44:45] op_sel_hi:[1,0]
	v_pk_mul_f32 v[66:67], v[4:5], v[72:73]
	v_pk_mul_f32 v[68:69], v[6:7], v[68:69]
	global_store_dwordx4 v[70:71], v[66:69], off
	v_mov_b32_e32 v62, v30
	v_mov_b32_e32 v63, v38
	s_waitcnt lgkmcnt(0)
; DI void final_norm_b(const Params& p) {
;     ...
;             const float rstd = rsqrtf(wave_sum(s) * (1.f / DM) + EPS);
;             float* dst = p.out + (size_t)row * DM + 8 * lane;
; #pragma unroll
;             for (int j = 0; j < 2; ++j) { *(f32x4*)(dst + 512 * j) = f[j][0] * rstd * gn[j][0]; *(f32x4*)(dst + 512 * j + 4) = f[j][1] * rstd * gn[j][1]; }
;         }
	v_pk_add_f32 v[68:69], v[52:53], v[54:55]
	s_nop 1
	v_mov_b32_dpp v73, v69 row_half_mirror row_mask:0xf bank_mask:0xf
	s_nop 1
	v_mov_b32_dpp v72, v68 row_half_mirror row_mask:0xf bank_mask:0xf
	v_mov_b32_e32 v66, v32
	v_mov_b32_e32 v67, v40
	v_pk_mul_f32 v[62:63], v[62:63], v[44:45] op_sel_hi:[1,0]
	v_pk_mul_f32 v[66:67], v[66:67], v[44:45] op_sel_hi:[1,0]
	v_pk_mul_f32 v[52:53], v[0:1], v[62:63]
	v_pk_mul_f32 v[54:55], v[2:3], v[66:67]
	v_mov_b32_e32 v28, v35
	s_waitcnt lgkmcnt(0)
	v_pk_add_f32 v[34:35], v[68:69], v[72:73]
	global_store_dwordx4 v[70:71], v[52:55], off offset:16
	s_nop 1
	v_mov_b32_dpp v53, v35 row_ror:8 row_mask:0xf bank_mask:0xf
	s_nop 1
	v_mov_b32_dpp v52, v34 row_ror:8 row_mask:0xf bank_mask:0xf
	v_mov_b32_e32 v42, v37
	v_pk_mul_f32 v[36:37], v[42:43], v[44:45] op_sel_hi:[1,0]
	v_pk_mul_f32 v[28:29], v[28:29], v[44:45] op_sel_hi:[1,0]
	v_pk_mul_f32 v[36:37], v[14:15], v[36:37]
	s_waitcnt lgkmcnt(0)
	v_pk_add_f32 v[42:43], v[34:35], v[52:53]
	ds_bpermute_b32 v53, v50, v43
	ds_bpermute_b32 v52, v50, v42
	v_pk_mul_f32 v[34:35], v[12:13], v[28:29]
	global_store_dwordx4 v[70:71], v[34:37], off offset:2048
	v_mov_b32_e32 v40, v33
	v_mov_b32_e32 v38, v31
	s_waitcnt lgkmcnt(0)
	v_pk_add_f32 v[34:35], v[42:43], v[52:53]
	ds_bpermute_b32 v37, v51, v35
	ds_bpermute_b32 v36, v51, v34
	v_pk_mul_f32 v[28:29], v[38:39], v[44:45] op_sel_hi:[1,0]
	v_pk_mul_f32 v[30:31], v[40:41], v[44:45] op_sel_hi:[1,0]
	v_pk_mul_f32 v[28:29], v[8:9], v[28:29]
	v_pk_mul_f32 v[30:31], v[10:11], v[30:31]
	s_waitcnt lgkmcnt(0)
	v_pk_add_f32 v[32:33], v[34:35], v[36:37]
	global_store_dwordx4 v[70:71], v[28:31], off offset:2064
	v_pk_fma_f32 v[32:33], v[32:33], s[8:9], v[20:21] op_sel_hi:[1,0,0]
	v_add_u32_e32 v44, s16, v22
	v_mul_f32_e32 v23, 0x4b800000, v33
	v_cmp_gt_f32_e32 vcc, s15, v33
	v_mov_b32_e32 v29, v76
	v_mov_b32_e32 v30, v78
	v_cndmask_b32_e32 v23, v33, v23, vcc
	v_rsq_f32_e32 v23, v23
	v_mov_b32_e32 v31, v80
	v_mov_b32_e32 v76, v75
	v_mov_b32_e32 v80, v79
	v_mul_f32_e32 v28, 0x45800000, v23
	v_cndmask_b32_e32 v34, v23, v28, vcc
	v_mov_b32_e32 v28, v74
	v_pk_mul_f32 v[28:29], v[28:29], v[34:35] op_sel_hi:[1,0]
	v_pk_mul_f32 v[30:31], v[30:31], v[34:35] op_sel_hi:[1,0]
	v_pk_mul_f32 v[28:29], v[4:5], v[28:29]
	v_pk_mul_f32 v[30:31], v[6:7], v[30:31]
	global_store_dwordx4 v[24:25], v[28:31], off
	v_mul_f32_e32 v23, 0x4b800000, v32
	v_cmp_gt_f32_e32 vcc, s15, v32
	v_mov_b32_e32 v28, v56
	v_mov_b32_e32 v29, v82
	v_mov_b32_e32 v30, v84
	v_mov_b32_e32 v31, v86
	v_pk_mul_f32 v[28:29], v[28:29], v[34:35] op_sel_hi:[1,0]
	v_pk_mul_f32 v[30:31], v[30:31], v[34:35] op_sel_hi:[1,0]
	v_pk_mul_f32 v[28:29], v[0:1], v[28:29]
	v_pk_mul_f32 v[30:31], v[2:3], v[30:31]
	v_cndmask_b32_e32 v23, v32, v23, vcc
	global_store_dwordx4 v[24:25], v[28:31], off offset:16
	v_rsq_f32_e32 v23, v23
	v_mov_b32_e32 v82, v57
	v_pk_mul_f32 v[28:29], v[76:77], v[34:35] op_sel_hi:[1,0]
	v_pk_mul_f32 v[30:31], v[80:81], v[34:35] op_sel_hi:[1,0]
	v_pk_mul_f32 v[28:29], v[12:13], v[28:29]
	v_pk_mul_f32 v[30:31], v[14:15], v[30:31]
	v_mov_b32_e32 v86, v85
	global_store_dwordx4 v[24:25], v[28:31], off offset:2048
	s_nop 1
	v_pk_mul_f32 v[28:29], v[82:83], v[34:35] op_sel_hi:[1,0]
	v_pk_mul_f32 v[30:31], v[86:87], v[34:35] op_sel_hi:[1,0]
	v_pk_mul_f32 v[28:29], v[8:9], v[28:29]
	v_pk_mul_f32 v[30:31], v[10:11], v[30:31]
	global_store_dwordx4 v[24:25], v[28:31], off offset:2064
	v_mul_f32_e32 v24, 0x45800000, v23
	s_nop 0
	v_cndmask_b32_e32 v28, v23, v24, vcc
	v_lshlrev_b64 v[24:25], 12, v[26:27]
	v_lshl_add_u64 v[30:31], v[18:19], 0, v[24:25]
	v_mov_b32_e32 v24, v58
	v_mov_b32_e32 v25, v88
	v_mov_b32_e32 v26, v90
	v_mov_b32_e32 v27, v64
	v_pk_mul_f32 v[24:25], v[24:25], v[28:29] op_sel_hi:[1,0]
	v_pk_mul_f32 v[26:27], v[26:27], v[28:29] op_sel_hi:[1,0]
	v_pk_mul_f32 v[24:25], v[4:5], v[24:25]
	v_pk_mul_f32 v[26:27], v[6:7], v[26:27]
	global_store_dwordx4 v[30:31], v[24:27], off
	v_mov_b32_e32 v88, v59
	v_mov_b32_e32 v64, v91
	v_mov_b32_e32 v24, v60
	v_mov_b32_e32 v25, v92
	v_mov_b32_e32 v26, v94
	v_mov_b32_e32 v27, v96
	v_pk_mul_f32 v[24:25], v[24:25], v[28:29] op_sel_hi:[1,0]
	v_pk_mul_f32 v[26:27], v[26:27], v[28:29] op_sel_hi:[1,0]
	v_pk_mul_f32 v[24:25], v[0:1], v[24:25]
	v_pk_mul_f32 v[26:27], v[2:3], v[26:27]
	global_store_dwordx4 v[30:31], v[24:27], off offset:16
	v_mov_b32_e32 v92, v61
	v_mov_b32_e32 v96, v95
	v_pk_mul_f32 v[24:25], v[88:89], v[28:29] op_sel_hi:[1,0]
	v_pk_mul_f32 v[26:27], v[64:65], v[28:29] op_sel_hi:[1,0]
	v_pk_mul_f32 v[24:25], v[12:13], v[24:25]
	v_pk_mul_f32 v[26:27], v[14:15], v[26:27]
	global_store_dwordx4 v[30:31], v[24:27], off offset:2048
	v_cmp_lt_i32_e32 vcc, s17, v44
	s_or_b64 s[6:7], vcc, s[6:7]
	v_pk_mul_f32 v[24:25], v[92:93], v[28:29] op_sel_hi:[1,0]
	v_pk_mul_f32 v[26:27], v[96:97], v[28:29] op_sel_hi:[1,0]
	v_pk_mul_f32 v[24:25], v[8:9], v[24:25]
	v_pk_mul_f32 v[26:27], v[10:11], v[26:27]
	global_store_dwordx4 v[30:31], v[24:27], off offset:2064
	s_andn2_b64 exec, exec, s[6:7]
	s_cbranch_execnz .LBB0_990
